# GEMM K-loops: dead m0 save/restore around each LDS-DMA removed
# baseline (speedup 1.0000x reference)
.LBB0_33:
	ds_read_b128 v[130:133], v155
	ds_read_b128 v[134:137], v155 offset:1024
	ds_read_b128 v[138:141], v155 offset:2048
	ds_read_b128 v[142:145], v155 offset:3072
	ds_read_b128 v[146:149], v156
	ds_read_b128 v[160:163], v156 offset:1024
	ds_read_b128 v[164:167], v156 offset:2048
	ds_read_b128 v[168:171], v156 offset:3072
	s_add_u32 s96, s44, 0x100
	s_addc_u32 s97, s45, 0
	s_cmp_eq_u32 s75, 28
	s_cselect_b32 s26, s70, s96
	s_cselect_b32 s27, s69, s97
	s_cselect_b32 s48, s72, s73
	s_cselect_b32 s49, s71, s74
	s_add_u32 s98, s26, 0x80
	s_addc_u32 s99, s27, 0
	ds_read_b128 v[172:175], v157
	ds_read_b128 v[176:179], v157 offset:1024
	ds_read_b128 v[180:183], v157 offset:2048
	ds_read_b128 v[184:187], v157 offset:3072
	ds_read_b128 v[188:191], v157 offset:4096
	ds_read_b128 v[192:195], v157 offset:5120
	ds_read_b128 v[196:199], v157 offset:6144
	ds_read_b128 v[200:203], v157 offset:7168
	s_add_u32 s44, s44, 0x80080
	s_addc_u32 s45, s45, 0
	s_mov_b32 m0, s54
	s_nop 0
	global_load_lds_dwordx4 v0, s[44:45]
	s_mov_b32 m0, s55
	s_nop 0
	global_load_lds_dwordx4 v151, s[44:45]
	s_waitcnt vmcnt(8)
	s_waitcnt lgkmcnt(0)
	s_barrier
	s_setprio 1
	s_waitcnt lgkmcnt(7)
	v_mfma_f32_16x16x32_bf16 v[126:129], v[130:133], v[172:175], v[126:129]
	v_mfma_f32_16x16x32_bf16 v[122:125], v[138:141], v[172:175], v[122:125]
	s_waitcnt lgkmcnt(5)
	v_mfma_f32_16x16x32_bf16 v[110:113], v[130:133], v[180:183], v[110:113]
	v_mfma_f32_16x16x32_bf16 v[106:109], v[138:141], v[180:183], v[106:109]
	s_waitcnt lgkmcnt(3)
	v_mfma_f32_16x16x32_bf16 v[94:97], v[130:133], v[188:191], v[94:97]
	v_mfma_f32_16x16x32_bf16 v[90:93], v[138:141], v[188:191], v[90:93]
	s_waitcnt lgkmcnt(1)
	v_mfma_f32_16x16x32_bf16 v[78:81], v[130:133], v[196:199], v[78:81]
	v_mfma_f32_16x16x32_bf16 v[74:77], v[138:141], v[196:199], v[74:77]
	v_mfma_f32_16x16x32_bf16 v[126:129], v[134:137], v[176:179], v[126:129]
	v_mfma_f32_16x16x32_bf16 v[122:125], v[142:145], v[176:179], v[122:125]
	v_mfma_f32_16x16x32_bf16 v[110:113], v[134:137], v[184:187], v[110:113]
	v_mfma_f32_16x16x32_bf16 v[106:109], v[142:145], v[184:187], v[106:109]
	v_mfma_f32_16x16x32_bf16 v[94:97], v[134:137], v[192:195], v[94:97]
	v_mfma_f32_16x16x32_bf16 v[90:93], v[142:145], v[192:195], v[90:93]
	s_waitcnt lgkmcnt(0)
	v_mfma_f32_16x16x32_bf16 v[78:81], v[134:137], v[200:203], v[78:81]
	v_mfma_f32_16x16x32_bf16 v[74:77], v[142:145], v[200:203], v[74:77]
	s_setprio 0
	s_setprio 1
	v_mfma_f32_16x16x32_bf16 v[118:121], v[146:149], v[172:175], v[118:121]
	v_mfma_f32_16x16x32_bf16 v[114:117], v[164:167], v[172:175], v[114:117]
	v_mfma_f32_16x16x32_bf16 v[102:105], v[146:149], v[180:183], v[102:105]
	v_mfma_f32_16x16x32_bf16 v[98:101], v[164:167], v[180:183], v[98:101]
	v_mfma_f32_16x16x32_bf16 v[86:89], v[146:149], v[188:191], v[86:89]
	v_mfma_f32_16x16x32_bf16 v[82:85], v[164:167], v[188:191], v[82:85]
	v_mfma_f32_16x16x32_bf16 v[70:73], v[146:149], v[196:199], v[70:73]
	v_mfma_f32_16x16x32_bf16 v[66:69], v[164:167], v[196:199], v[66:69]
	v_mfma_f32_16x16x32_bf16 v[118:121], v[160:163], v[176:179], v[118:121]
	v_mfma_f32_16x16x32_bf16 v[114:117], v[168:171], v[176:179], v[114:117]
	v_mfma_f32_16x16x32_bf16 v[102:105], v[160:163], v[184:187], v[102:105]
	v_mfma_f32_16x16x32_bf16 v[98:101], v[168:171], v[184:187], v[98:101]
	v_mfma_f32_16x16x32_bf16 v[86:89], v[160:163], v[192:195], v[86:89]
	v_mfma_f32_16x16x32_bf16 v[82:85], v[168:171], v[192:195], v[82:85]
	v_mfma_f32_16x16x32_bf16 v[70:73], v[160:163], v[200:203], v[70:73]
	v_mfma_f32_16x16x32_bf16 v[66:69], v[168:171], v[200:203], v[66:69]
	s_setprio 0
	s_barrier
	ds_read_b128 v[172:175], v157 offset:16384
	ds_read_b128 v[176:179], v157 offset:17408
	ds_read_b128 v[180:183], v157 offset:18432
	ds_read_b128 v[184:187], v157 offset:19456
	ds_read_b128 v[188:191], v157 offset:20480
	ds_read_b128 v[192:195], v157 offset:21504
	ds_read_b128 v[196:199], v157 offset:22528
	ds_read_b128 v[200:203], v157 offset:23552
	s_mov_b32 m0, s16
	s_nop 0
	global_load_lds_dwordx4 v150, s[48:49]
	s_mov_b32 m0, s17
	s_nop 0
	global_load_lds_dwordx4 v152, s[48:49]
	s_add_u32 s44, s48, 0x80000
	s_addc_u32 s45, s49, 0
	s_mov_b32 m0, s18
	s_nop 0
	global_load_lds_dwordx4 v150, s[44:45]
	s_mov_b32 m0, s19
	s_nop 0
	global_load_lds_dwordx4 v152, s[44:45]
	s_mov_b32 m0, s11
	s_nop 0
	global_load_lds_dwordx4 v0, s[26:27]
	s_mov_b32 m0, s20
	s_nop 0
	global_load_lds_dwordx4 v151, s[26:27]
	s_waitcnt vmcnt(8)
	s_waitcnt lgkmcnt(0)
	s_barrier
	s_setprio 1
	s_waitcnt lgkmcnt(7)
	v_mfma_f32_16x16x32_bf16 v[62:65], v[130:133], v[172:175], v[62:65]
	v_mfma_f32_16x16x32_bf16 v[58:61], v[138:141], v[172:175], v[58:61]
	s_waitcnt lgkmcnt(5)
	v_mfma_f32_16x16x32_bf16 v[46:49], v[130:133], v[180:183], v[46:49]
	v_mfma_f32_16x16x32_bf16 v[42:45], v[138:141], v[180:183], v[42:45]
	s_waitcnt lgkmcnt(3)
	v_mfma_f32_16x16x32_bf16 v[30:33], v[130:133], v[188:191], v[30:33]
	v_mfma_f32_16x16x32_bf16 v[26:29], v[138:141], v[188:191], v[26:29]
	s_waitcnt lgkmcnt(1)
	v_mfma_f32_16x16x32_bf16 v[14:17], v[130:133], v[196:199], v[14:17]
	v_mfma_f32_16x16x32_bf16 v[10:13], v[138:141], v[196:199], v[10:13]
	v_mfma_f32_16x16x32_bf16 v[62:65], v[134:137], v[176:179], v[62:65]
	v_mfma_f32_16x16x32_bf16 v[58:61], v[142:145], v[176:179], v[58:61]
	v_mfma_f32_16x16x32_bf16 v[46:49], v[134:137], v[184:187], v[46:49]
	v_mfma_f32_16x16x32_bf16 v[42:45], v[142:145], v[184:187], v[42:45]
	v_mfma_f32_16x16x32_bf16 v[30:33], v[134:137], v[192:195], v[30:33]
	v_mfma_f32_16x16x32_bf16 v[26:29], v[142:145], v[192:195], v[26:29]
	s_waitcnt lgkmcnt(0)
	v_mfma_f32_16x16x32_bf16 v[14:17], v[134:137], v[200:203], v[14:17]
	v_mfma_f32_16x16x32_bf16 v[10:13], v[142:145], v[200:203], v[10:13]
	s_setprio 0
	s_setprio 1
	v_mfma_f32_16x16x32_bf16 v[54:57], v[146:149], v[172:175], v[54:57]
	v_mfma_f32_16x16x32_bf16 v[50:53], v[164:167], v[172:175], v[50:53]
	v_mfma_f32_16x16x32_bf16 v[38:41], v[146:149], v[180:183], v[38:41]
	v_mfma_f32_16x16x32_bf16 v[34:37], v[164:167], v[180:183], v[34:37]
	v_mfma_f32_16x16x32_bf16 v[22:25], v[146:149], v[188:191], v[22:25]
	v_mfma_f32_16x16x32_bf16 v[18:21], v[164:167], v[188:191], v[18:21]
	v_mfma_f32_16x16x32_bf16 v[6:9], v[146:149], v[196:199], v[6:9]
	v_mfma_f32_16x16x32_bf16 v[2:5], v[164:167], v[196:199], v[2:5]
	v_mfma_f32_16x16x32_bf16 v[54:57], v[160:163], v[176:179], v[54:57]
	v_mfma_f32_16x16x32_bf16 v[50:53], v[168:171], v[176:179], v[50:53]
	v_mfma_f32_16x16x32_bf16 v[38:41], v[160:163], v[184:187], v[38:41]
	v_mfma_f32_16x16x32_bf16 v[34:37], v[168:171], v[184:187], v[34:37]
	v_mfma_f32_16x16x32_bf16 v[22:25], v[160:163], v[192:195], v[22:25]
	v_mfma_f32_16x16x32_bf16 v[18:21], v[168:171], v[192:195], v[18:21]
	v_mfma_f32_16x16x32_bf16 v[6:9], v[160:163], v[200:203], v[6:9]
	v_mfma_f32_16x16x32_bf16 v[2:5], v[168:171], v[200:203], v[2:5]
	s_setprio 0
	s_barrier
	ds_read_b128 v[130:133], v158
	ds_read_b128 v[134:137], v158 offset:1024
	ds_read_b128 v[138:141], v158 offset:2048
	ds_read_b128 v[142:145], v158 offset:3072
	ds_read_b128 v[146:149], v159
	ds_read_b128 v[160:163], v159 offset:1024
	ds_read_b128 v[164:167], v159 offset:2048
	ds_read_b128 v[168:171], v159 offset:3072
	ds_read_b128 v[172:175], v157 offset:32768
	ds_read_b128 v[176:179], v157 offset:33792
	ds_read_b128 v[180:183], v157 offset:34816
	ds_read_b128 v[184:187], v157 offset:35840
	ds_read_b128 v[188:191], v157 offset:36864
	ds_read_b128 v[192:195], v157 offset:37888
	ds_read_b128 v[196:199], v157 offset:38912
	ds_read_b128 v[200:203], v157 offset:39936
	s_add_u32 s26, s26, 0x80000
	s_addc_u32 s27, s27, 0
	s_mov_b32 m0, s21
	s_nop 0
	global_load_lds_dwordx4 v0, s[26:27]
	s_mov_b32 m0, s22
	s_nop 0
	global_load_lds_dwordx4 v151, s[26:27]
	s_waitcnt vmcnt(8)
	s_waitcnt lgkmcnt(0)
	s_barrier
	s_setprio 1
	s_waitcnt lgkmcnt(7)
	v_mfma_f32_16x16x32_bf16 v[126:129], v[130:133], v[172:175], v[126:129]
	v_mfma_f32_16x16x32_bf16 v[122:125], v[138:141], v[172:175], v[122:125]
	s_waitcnt lgkmcnt(5)
	v_mfma_f32_16x16x32_bf16 v[110:113], v[130:133], v[180:183], v[110:113]
	v_mfma_f32_16x16x32_bf16 v[106:109], v[138:141], v[180:183], v[106:109]
	s_waitcnt lgkmcnt(3)
	v_mfma_f32_16x16x32_bf16 v[94:97], v[130:133], v[188:191], v[94:97]
	v_mfma_f32_16x16x32_bf16 v[90:93], v[138:141], v[188:191], v[90:93]
	s_waitcnt lgkmcnt(1)
	v_mfma_f32_16x16x32_bf16 v[78:81], v[130:133], v[196:199], v[78:81]
	v_mfma_f32_16x16x32_bf16 v[74:77], v[138:141], v[196:199], v[74:77]
	v_mfma_f32_16x16x32_bf16 v[126:129], v[134:137], v[176:179], v[126:129]
	v_mfma_f32_16x16x32_bf16 v[122:125], v[142:145], v[176:179], v[122:125]
	v_mfma_f32_16x16x32_bf16 v[110:113], v[134:137], v[184:187], v[110:113]
	v_mfma_f32_16x16x32_bf16 v[106:109], v[142:145], v[184:187], v[106:109]
	v_mfma_f32_16x16x32_bf16 v[94:97], v[134:137], v[192:195], v[94:97]
	v_mfma_f32_16x16x32_bf16 v[90:93], v[142:145], v[192:195], v[90:93]
	s_waitcnt lgkmcnt(0)
	v_mfma_f32_16x16x32_bf16 v[78:81], v[134:137], v[200:203], v[78:81]
	v_mfma_f32_16x16x32_bf16 v[74:77], v[142:145], v[200:203], v[74:77]
	s_setprio 0
	s_setprio 1
	v_mfma_f32_16x16x32_bf16 v[118:121], v[146:149], v[172:175], v[118:121]
	v_mfma_f32_16x16x32_bf16 v[114:117], v[164:167], v[172:175], v[114:117]
	v_mfma_f32_16x16x32_bf16 v[102:105], v[146:149], v[180:183], v[102:105]
	v_mfma_f32_16x16x32_bf16 v[98:101], v[164:167], v[180:183], v[98:101]
	v_mfma_f32_16x16x32_bf16 v[86:89], v[146:149], v[188:191], v[86:89]
	v_mfma_f32_16x16x32_bf16 v[82:85], v[164:167], v[188:191], v[82:85]
	v_mfma_f32_16x16x32_bf16 v[70:73], v[146:149], v[196:199], v[70:73]
	v_mfma_f32_16x16x32_bf16 v[66:69], v[164:167], v[196:199], v[66:69]
	v_mfma_f32_16x16x32_bf16 v[118:121], v[160:163], v[176:179], v[118:121]
	v_mfma_f32_16x16x32_bf16 v[114:117], v[168:171], v[176:179], v[114:117]
	v_mfma_f32_16x16x32_bf16 v[102:105], v[160:163], v[184:187], v[102:105]
	v_mfma_f32_16x16x32_bf16 v[98:101], v[168:171], v[184:187], v[98:101]
	v_mfma_f32_16x16x32_bf16 v[86:89], v[160:163], v[192:195], v[86:89]
	v_mfma_f32_16x16x32_bf16 v[82:85], v[168:171], v[192:195], v[82:85]
	v_mfma_f32_16x16x32_bf16 v[70:73], v[160:163], v[200:203], v[70:73]
	v_mfma_f32_16x16x32_bf16 v[66:69], v[168:171], v[200:203], v[66:69]
	s_setprio 0
	s_barrier
	ds_read_b128 v[172:175], v157 offset:49152
	ds_read_b128 v[176:179], v157 offset:50176
	ds_read_b128 v[180:183], v157 offset:51200
	ds_read_b128 v[184:187], v157 offset:52224
	ds_read_b128 v[188:191], v157 offset:53248
	ds_read_b128 v[192:195], v157 offset:54272
	ds_read_b128 v[196:199], v157 offset:55296
	ds_read_b128 v[200:203], v157 offset:56320
	s_add_u32 s26, s48, 0x80
	s_addc_u32 s27, s49, 0
	s_mov_b32 m0, s31
	s_nop 0
	global_load_lds_dwordx4 v150, s[26:27]
	s_mov_b32 m0, s33
	s_nop 0
	global_load_lds_dwordx4 v152, s[26:27]
	s_add_u32 s26, s48, 0x80080
	s_addc_u32 s27, s49, 0
	s_mov_b32 m0, s46
	s_nop 0
	global_load_lds_dwordx4 v150, s[26:27]
	s_mov_b32 m0, s47
	s_nop 0
	global_load_lds_dwordx4 v152, s[26:27]
	s_mov_b32 m0, s36
	s_nop 0
	global_load_lds_dwordx4 v0, s[98:99]
	s_mov_b32 m0, s37
	s_nop 0
	global_load_lds_dwordx4 v151, s[98:99]
	s_waitcnt vmcnt(8)
	s_waitcnt lgkmcnt(0)
	s_barrier
	s_setprio 1
	s_waitcnt lgkmcnt(7)
	v_mfma_f32_16x16x32_bf16 v[62:65], v[130:133], v[172:175], v[62:65]
	v_mfma_f32_16x16x32_bf16 v[58:61], v[138:141], v[172:175], v[58:61]
	s_waitcnt lgkmcnt(5)
	v_mfma_f32_16x16x32_bf16 v[46:49], v[130:133], v[180:183], v[46:49]
	v_mfma_f32_16x16x32_bf16 v[42:45], v[138:141], v[180:183], v[42:45]
	s_waitcnt lgkmcnt(3)
	v_mfma_f32_16x16x32_bf16 v[30:33], v[130:133], v[188:191], v[30:33]
	v_mfma_f32_16x16x32_bf16 v[26:29], v[138:141], v[188:191], v[26:29]
	s_waitcnt lgkmcnt(1)
	v_mfma_f32_16x16x32_bf16 v[14:17], v[130:133], v[196:199], v[14:17]
	v_mfma_f32_16x16x32_bf16 v[10:13], v[138:141], v[196:199], v[10:13]
	v_mfma_f32_16x16x32_bf16 v[62:65], v[134:137], v[176:179], v[62:65]
	v_mfma_f32_16x16x32_bf16 v[58:61], v[142:145], v[176:179], v[58:61]
	v_mfma_f32_16x16x32_bf16 v[46:49], v[134:137], v[184:187], v[46:49]
	v_mfma_f32_16x16x32_bf16 v[42:45], v[142:145], v[184:187], v[42:45]
	v_mfma_f32_16x16x32_bf16 v[30:33], v[134:137], v[192:195], v[30:33]
	v_mfma_f32_16x16x32_bf16 v[26:29], v[142:145], v[192:195], v[26:29]
	s_waitcnt lgkmcnt(0)
	v_mfma_f32_16x16x32_bf16 v[14:17], v[134:137], v[200:203], v[14:17]
	v_mfma_f32_16x16x32_bf16 v[10:13], v[142:145], v[200:203], v[10:13]
	s_setprio 0
	s_setprio 1
	v_mfma_f32_16x16x32_bf16 v[54:57], v[146:149], v[172:175], v[54:57]
	v_mfma_f32_16x16x32_bf16 v[50:53], v[164:167], v[172:175], v[50:53]
	v_mfma_f32_16x16x32_bf16 v[38:41], v[146:149], v[180:183], v[38:41]
	v_mfma_f32_16x16x32_bf16 v[34:37], v[164:167], v[180:183], v[34:37]
	v_mfma_f32_16x16x32_bf16 v[22:25], v[146:149], v[188:191], v[22:25]
	v_mfma_f32_16x16x32_bf16 v[18:21], v[164:167], v[188:191], v[18:21]
	v_mfma_f32_16x16x32_bf16 v[6:9], v[146:149], v[196:199], v[6:9]
	v_mfma_f32_16x16x32_bf16 v[2:5], v[164:167], v[196:199], v[2:5]
	v_mfma_f32_16x16x32_bf16 v[54:57], v[160:163], v[176:179], v[54:57]
	v_mfma_f32_16x16x32_bf16 v[50:53], v[168:171], v[176:179], v[50:53]
	v_mfma_f32_16x16x32_bf16 v[38:41], v[160:163], v[184:187], v[38:41]
	v_mfma_f32_16x16x32_bf16 v[34:37], v[168:171], v[184:187], v[34:37]
	v_mfma_f32_16x16x32_bf16 v[22:25], v[160:163], v[192:195], v[22:25]
	v_mfma_f32_16x16x32_bf16 v[18:21], v[168:171], v[192:195], v[18:21]
	v_mfma_f32_16x16x32_bf16 v[6:9], v[160:163], v[200:203], v[6:9]
	v_mfma_f32_16x16x32_bf16 v[2:5], v[168:171], v[200:203], v[2:5]
	s_setprio 0
	s_barrier
	s_add_i32 s75, s75, 2
	s_add_u32 s73, s73, 0x100
	s_addc_u32 s74, s74, 0
	s_cmp_gt_u32 s75, 29
	s_mov_b64 s[44:45], s[96:97]
	s_cbranch_scc0 .LBB0_33
	s_and_b64 vcc, exec, s[60:61]
	s_cbranch_vccz .LBB0_36
	s_barrier

.LBB0_367:
	v_add_u32_e32 v0, 0x10000, v150
	ds_read_b128 v[130:133], v0
	ds_read_b128 v[134:137], v0 offset:1024
	ds_read_b128 v[138:141], v0 offset:2048
	ds_read_b128 v[152:155], v0 offset:3072
	v_add_u32_e32 v0, 0x14000, v150
	ds_read_b128 v[156:159], v0
	ds_read_b128 v[160:163], v0 offset:1024
	ds_read_b128 v[164:167], v0 offset:2048
	ds_read_b128 v[168:171], v0 offset:3072
	s_add_u32 s46, s44, 0x100
	s_addc_u32 s47, s45, 0
	s_cmp_eq_u32 s73, 12
	s_cselect_b32 s48, s27, s46
	s_cselect_b32 s49, s26, s47
	s_cselect_b32 s98, s70, s71
	s_cselect_b32 s99, s69, s72
	s_add_u32 s96, s48, 0x80
	s_addc_u32 s97, s49, 0
	ds_read_b128 v[172:175], v151
	ds_read_b128 v[176:179], v151 offset:1024
	ds_read_b128 v[180:183], v151 offset:2048
	ds_read_b128 v[184:187], v151 offset:3072
	ds_read_b128 v[188:191], v151 offset:4096
	ds_read_b128 v[192:195], v151 offset:5120
	ds_read_b128 v[196:199], v151 offset:6144
	ds_read_b128 v[200:203], v151 offset:7168
	s_add_u32 s44, s44, 0x40080
	s_addc_u32 s45, s45, 0
	s_mov_b32 m0, s56
	s_nop 0
	global_load_lds_dwordx4 v144, s[44:45]
	s_mov_b32 m0, s18
	s_nop 0
	global_load_lds_dwordx4 v146, s[44:45]
	s_waitcnt vmcnt(8)
	s_waitcnt lgkmcnt(0)
	s_barrier
	s_setprio 1
	s_waitcnt lgkmcnt(7)
	v_mfma_f32_16x16x32_bf16 v[126:129], v[130:133], v[172:175], v[126:129]
	v_mfma_f32_16x16x32_bf16 v[122:125], v[138:141], v[172:175], v[122:125]
	s_waitcnt lgkmcnt(5)
	v_mfma_f32_16x16x32_bf16 v[110:113], v[130:133], v[180:183], v[110:113]
	v_mfma_f32_16x16x32_bf16 v[106:109], v[138:141], v[180:183], v[106:109]
	s_waitcnt lgkmcnt(3)
	v_mfma_f32_16x16x32_bf16 v[94:97], v[130:133], v[188:191], v[94:97]
	v_mfma_f32_16x16x32_bf16 v[90:93], v[138:141], v[188:191], v[90:93]
	s_waitcnt lgkmcnt(1)
	v_mfma_f32_16x16x32_bf16 v[78:81], v[130:133], v[196:199], v[78:81]
	v_mfma_f32_16x16x32_bf16 v[74:77], v[138:141], v[196:199], v[74:77]
	v_mfma_f32_16x16x32_bf16 v[126:129], v[134:137], v[176:179], v[126:129]
	v_mfma_f32_16x16x32_bf16 v[122:125], v[152:155], v[176:179], v[122:125]
	v_mfma_f32_16x16x32_bf16 v[110:113], v[134:137], v[184:187], v[110:113]
	v_mfma_f32_16x16x32_bf16 v[106:109], v[152:155], v[184:187], v[106:109]
	v_mfma_f32_16x16x32_bf16 v[94:97], v[134:137], v[192:195], v[94:97]
	v_mfma_f32_16x16x32_bf16 v[90:93], v[152:155], v[192:195], v[90:93]
	s_waitcnt lgkmcnt(0)
	v_mfma_f32_16x16x32_bf16 v[78:81], v[134:137], v[200:203], v[78:81]
	v_mfma_f32_16x16x32_bf16 v[74:77], v[152:155], v[200:203], v[74:77]
	s_setprio 0
	s_setprio 1
	v_mfma_f32_16x16x32_bf16 v[118:121], v[156:159], v[172:175], v[118:121]
	v_mfma_f32_16x16x32_bf16 v[114:117], v[164:167], v[172:175], v[114:117]
	v_mfma_f32_16x16x32_bf16 v[102:105], v[156:159], v[180:183], v[102:105]
	v_mfma_f32_16x16x32_bf16 v[98:101], v[164:167], v[180:183], v[98:101]
	v_mfma_f32_16x16x32_bf16 v[86:89], v[156:159], v[188:191], v[86:89]
	v_mfma_f32_16x16x32_bf16 v[82:85], v[164:167], v[188:191], v[82:85]
	v_mfma_f32_16x16x32_bf16 v[70:73], v[156:159], v[196:199], v[70:73]
	v_mfma_f32_16x16x32_bf16 v[66:69], v[164:167], v[196:199], v[66:69]
	v_mfma_f32_16x16x32_bf16 v[118:121], v[160:163], v[176:179], v[118:121]
	v_mfma_f32_16x16x32_bf16 v[114:117], v[168:171], v[176:179], v[114:117]
	v_mfma_f32_16x16x32_bf16 v[102:105], v[160:163], v[184:187], v[102:105]
	v_mfma_f32_16x16x32_bf16 v[98:101], v[168:171], v[184:187], v[98:101]
	v_mfma_f32_16x16x32_bf16 v[86:89], v[160:163], v[192:195], v[86:89]
	v_mfma_f32_16x16x32_bf16 v[82:85], v[168:171], v[192:195], v[82:85]
	v_mfma_f32_16x16x32_bf16 v[70:73], v[160:163], v[200:203], v[70:73]
	v_mfma_f32_16x16x32_bf16 v[66:69], v[168:171], v[200:203], v[66:69]
	s_setprio 0
	s_barrier
	ds_read_b128 v[172:175], v151 offset:16384
	ds_read_b128 v[176:179], v151 offset:17408
	ds_read_b128 v[180:183], v151 offset:18432
	ds_read_b128 v[184:187], v151 offset:19456
	ds_read_b128 v[188:191], v151 offset:20480
	ds_read_b128 v[192:195], v151 offset:21504
	ds_read_b128 v[196:199], v151 offset:22528
	ds_read_b128 v[200:203], v151 offset:23552
	s_mov_b32 m0, s22
	s_nop 0
	global_load_lds_dwordx4 v145, s[98:99]
	s_mov_b32 m0, s23
	s_nop 0
	global_load_lds_dwordx4 v147, s[98:99]
	s_add_u32 s44, s98, 0x40000
	s_addc_u32 s45, s99, 0
	s_mov_b32 m0, s54
	s_nop 0
	global_load_lds_dwordx4 v145, s[44:45]
	s_mov_b32 m0, s55
	s_nop 0
	global_load_lds_dwordx4 v147, s[44:45]
	s_mov_b32 m0, s28
	s_nop 0
	global_load_lds_dwordx4 v144, s[48:49]
	s_mov_b32 m0, s6
	s_nop 0
	global_load_lds_dwordx4 v146, s[48:49]
	s_waitcnt vmcnt(8)
	s_waitcnt lgkmcnt(0)
	s_barrier
	s_setprio 1
	s_waitcnt lgkmcnt(7)
	v_mfma_f32_16x16x32_bf16 v[62:65], v[130:133], v[172:175], v[62:65]
	v_mfma_f32_16x16x32_bf16 v[58:61], v[138:141], v[172:175], v[58:61]
	s_waitcnt lgkmcnt(5)
	v_mfma_f32_16x16x32_bf16 v[46:49], v[130:133], v[180:183], v[46:49]
	v_mfma_f32_16x16x32_bf16 v[42:45], v[138:141], v[180:183], v[42:45]
	s_waitcnt lgkmcnt(3)
	v_mfma_f32_16x16x32_bf16 v[30:33], v[130:133], v[188:191], v[30:33]
	v_mfma_f32_16x16x32_bf16 v[26:29], v[138:141], v[188:191], v[26:29]
	s_waitcnt lgkmcnt(1)
	v_mfma_f32_16x16x32_bf16 v[14:17], v[130:133], v[196:199], v[14:17]
	v_mfma_f32_16x16x32_bf16 v[10:13], v[138:141], v[196:199], v[10:13]
	v_mfma_f32_16x16x32_bf16 v[62:65], v[134:137], v[176:179], v[62:65]
	v_mfma_f32_16x16x32_bf16 v[58:61], v[152:155], v[176:179], v[58:61]
	v_mfma_f32_16x16x32_bf16 v[46:49], v[134:137], v[184:187], v[46:49]
	v_mfma_f32_16x16x32_bf16 v[42:45], v[152:155], v[184:187], v[42:45]
	v_mfma_f32_16x16x32_bf16 v[30:33], v[134:137], v[192:195], v[30:33]
	v_mfma_f32_16x16x32_bf16 v[26:29], v[152:155], v[192:195], v[26:29]
	s_waitcnt lgkmcnt(0)
	v_mfma_f32_16x16x32_bf16 v[14:17], v[134:137], v[200:203], v[14:17]
	v_mfma_f32_16x16x32_bf16 v[10:13], v[152:155], v[200:203], v[10:13]
	s_setprio 0
	s_setprio 1
	v_mfma_f32_16x16x32_bf16 v[54:57], v[156:159], v[172:175], v[54:57]
	v_mfma_f32_16x16x32_bf16 v[50:53], v[164:167], v[172:175], v[50:53]
	v_mfma_f32_16x16x32_bf16 v[38:41], v[156:159], v[180:183], v[38:41]
	v_mfma_f32_16x16x32_bf16 v[34:37], v[164:167], v[180:183], v[34:37]
	v_mfma_f32_16x16x32_bf16 v[22:25], v[156:159], v[188:191], v[22:25]
	v_mfma_f32_16x16x32_bf16 v[18:21], v[164:167], v[188:191], v[18:21]
	v_mfma_f32_16x16x32_bf16 v[6:9], v[156:159], v[196:199], v[6:9]
	v_mfma_f32_16x16x32_bf16 v[2:5], v[164:167], v[196:199], v[2:5]
	v_mfma_f32_16x16x32_bf16 v[54:57], v[160:163], v[176:179], v[54:57]
	v_mfma_f32_16x16x32_bf16 v[50:53], v[168:171], v[176:179], v[50:53]
	v_mfma_f32_16x16x32_bf16 v[38:41], v[160:163], v[184:187], v[38:41]
	v_mfma_f32_16x16x32_bf16 v[34:37], v[168:171], v[184:187], v[34:37]
	v_mfma_f32_16x16x32_bf16 v[22:25], v[160:163], v[192:195], v[22:25]
	v_mfma_f32_16x16x32_bf16 v[18:21], v[168:171], v[192:195], v[18:21]
	v_mfma_f32_16x16x32_bf16 v[6:9], v[160:163], v[200:203], v[6:9]
	v_mfma_f32_16x16x32_bf16 v[2:5], v[168:171], v[200:203], v[2:5]
	s_setprio 0
	s_barrier
	v_add_u32_e32 v0, 0x18000, v150
	ds_read_b128 v[130:133], v0
	ds_read_b128 v[134:137], v0 offset:1024
	ds_read_b128 v[138:141], v0 offset:2048
	ds_read_b128 v[152:155], v0 offset:3072
	v_add_u32_e32 v0, 0x1c000, v150
	ds_read_b128 v[156:159], v0
	ds_read_b128 v[160:163], v0 offset:1024
	ds_read_b128 v[164:167], v0 offset:2048
	ds_read_b128 v[168:171], v0 offset:3072
	ds_read_b128 v[172:175], v151 offset:32768
	ds_read_b128 v[176:179], v151 offset:33792
	ds_read_b128 v[180:183], v151 offset:34816
	ds_read_b128 v[184:187], v151 offset:35840
	ds_read_b128 v[188:191], v151 offset:36864
	ds_read_b128 v[192:195], v151 offset:37888
	ds_read_b128 v[196:199], v151 offset:38912
	ds_read_b128 v[200:203], v151 offset:39936
	s_add_u32 s44, s48, 0x40000
	s_addc_u32 s45, s49, 0
	s_mov_b32 m0, s33
	s_nop 0
	global_load_lds_dwordx4 v144, s[44:45]
	s_mov_b32 m0, s16
	s_nop 0
	global_load_lds_dwordx4 v146, s[44:45]
	s_waitcnt vmcnt(8)
	s_waitcnt lgkmcnt(0)
	s_barrier
	s_setprio 1
	s_waitcnt lgkmcnt(7)
	v_mfma_f32_16x16x32_bf16 v[126:129], v[130:133], v[172:175], v[126:129]
	v_mfma_f32_16x16x32_bf16 v[122:125], v[138:141], v[172:175], v[122:125]
	s_waitcnt lgkmcnt(5)
	v_mfma_f32_16x16x32_bf16 v[110:113], v[130:133], v[180:183], v[110:113]
	v_mfma_f32_16x16x32_bf16 v[106:109], v[138:141], v[180:183], v[106:109]
	s_waitcnt lgkmcnt(3)
	v_mfma_f32_16x16x32_bf16 v[94:97], v[130:133], v[188:191], v[94:97]
	v_mfma_f32_16x16x32_bf16 v[90:93], v[138:141], v[188:191], v[90:93]
	s_waitcnt lgkmcnt(1)
	v_mfma_f32_16x16x32_bf16 v[78:81], v[130:133], v[196:199], v[78:81]
	v_mfma_f32_16x16x32_bf16 v[74:77], v[138:141], v[196:199], v[74:77]
	v_mfma_f32_16x16x32_bf16 v[126:129], v[134:137], v[176:179], v[126:129]
	v_mfma_f32_16x16x32_bf16 v[122:125], v[152:155], v[176:179], v[122:125]
	v_mfma_f32_16x16x32_bf16 v[110:113], v[134:137], v[184:187], v[110:113]
	v_mfma_f32_16x16x32_bf16 v[106:109], v[152:155], v[184:187], v[106:109]
	v_mfma_f32_16x16x32_bf16 v[94:97], v[134:137], v[192:195], v[94:97]
	v_mfma_f32_16x16x32_bf16 v[90:93], v[152:155], v[192:195], v[90:93]
	s_waitcnt lgkmcnt(0)
	v_mfma_f32_16x16x32_bf16 v[78:81], v[134:137], v[200:203], v[78:81]
	v_mfma_f32_16x16x32_bf16 v[74:77], v[152:155], v[200:203], v[74:77]
	s_setprio 0
	s_setprio 1
	v_mfma_f32_16x16x32_bf16 v[118:121], v[156:159], v[172:175], v[118:121]
	v_mfma_f32_16x16x32_bf16 v[114:117], v[164:167], v[172:175], v[114:117]
	v_mfma_f32_16x16x32_bf16 v[102:105], v[156:159], v[180:183], v[102:105]
	v_mfma_f32_16x16x32_bf16 v[98:101], v[164:167], v[180:183], v[98:101]
	v_mfma_f32_16x16x32_bf16 v[86:89], v[156:159], v[188:191], v[86:89]
	v_mfma_f32_16x16x32_bf16 v[82:85], v[164:167], v[188:191], v[82:85]
	v_mfma_f32_16x16x32_bf16 v[70:73], v[156:159], v[196:199], v[70:73]
	v_mfma_f32_16x16x32_bf16 v[66:69], v[164:167], v[196:199], v[66:69]
	v_mfma_f32_16x16x32_bf16 v[118:121], v[160:163], v[176:179], v[118:121]
	v_mfma_f32_16x16x32_bf16 v[114:117], v[168:171], v[176:179], v[114:117]
	v_mfma_f32_16x16x32_bf16 v[102:105], v[160:163], v[184:187], v[102:105]
	v_mfma_f32_16x16x32_bf16 v[98:101], v[168:171], v[184:187], v[98:101]
	v_mfma_f32_16x16x32_bf16 v[86:89], v[160:163], v[192:195], v[86:89]
	v_mfma_f32_16x16x32_bf16 v[82:85], v[168:171], v[192:195], v[82:85]
	v_mfma_f32_16x16x32_bf16 v[70:73], v[160:163], v[200:203], v[70:73]
	v_mfma_f32_16x16x32_bf16 v[66:69], v[168:171], v[200:203], v[66:69]
	s_setprio 0
	s_barrier
	ds_read_b128 v[172:175], v151 offset:49152
	ds_read_b128 v[176:179], v151 offset:50176
	ds_read_b128 v[180:183], v151 offset:51200
	ds_read_b128 v[184:187], v151 offset:52224
	ds_read_b128 v[188:191], v151 offset:53248
	ds_read_b128 v[192:195], v151 offset:54272
	ds_read_b128 v[196:199], v151 offset:55296
	ds_read_b128 v[200:203], v151 offset:56320
	s_add_u32 s44, s98, 0x80
	s_addc_u32 s45, s99, 0
	s_mov_b32 m0, s2
	s_nop 0
	global_load_lds_dwordx4 v145, s[44:45]
	s_mov_b32 m0, s10
	s_nop 0
	global_load_lds_dwordx4 v147, s[44:45]
	s_add_u32 s44, s98, 0x40080
	s_addc_u32 s45, s99, 0
	s_mov_b32 m0, s21
	s_nop 0
	global_load_lds_dwordx4 v145, s[44:45]
	s_mov_b32 m0, s31
	s_nop 0
	global_load_lds_dwordx4 v147, s[44:45]
	s_mov_b32 m0, s11
	s_nop 0
	global_load_lds_dwordx4 v144, s[96:97]
	s_mov_b32 m0, s20
	s_nop 0
	global_load_lds_dwordx4 v146, s[96:97]
	s_waitcnt vmcnt(8)
	s_waitcnt lgkmcnt(0)
	s_barrier
	s_setprio 1
	s_waitcnt lgkmcnt(7)
	v_mfma_f32_16x16x32_bf16 v[62:65], v[130:133], v[172:175], v[62:65]
	v_mfma_f32_16x16x32_bf16 v[58:61], v[138:141], v[172:175], v[58:61]
	s_waitcnt lgkmcnt(5)
	v_mfma_f32_16x16x32_bf16 v[46:49], v[130:133], v[180:183], v[46:49]
	v_mfma_f32_16x16x32_bf16 v[42:45], v[138:141], v[180:183], v[42:45]
	s_waitcnt lgkmcnt(3)
	v_mfma_f32_16x16x32_bf16 v[30:33], v[130:133], v[188:191], v[30:33]
	v_mfma_f32_16x16x32_bf16 v[26:29], v[138:141], v[188:191], v[26:29]
	s_waitcnt lgkmcnt(1)
	v_mfma_f32_16x16x32_bf16 v[14:17], v[130:133], v[196:199], v[14:17]
	v_mfma_f32_16x16x32_bf16 v[10:13], v[138:141], v[196:199], v[10:13]
	v_mfma_f32_16x16x32_bf16 v[62:65], v[134:137], v[176:179], v[62:65]
	v_mfma_f32_16x16x32_bf16 v[58:61], v[152:155], v[176:179], v[58:61]
	v_mfma_f32_16x16x32_bf16 v[46:49], v[134:137], v[184:187], v[46:49]
	v_mfma_f32_16x16x32_bf16 v[42:45], v[152:155], v[184:187], v[42:45]
	v_mfma_f32_16x16x32_bf16 v[30:33], v[134:137], v[192:195], v[30:33]
	v_mfma_f32_16x16x32_bf16 v[26:29], v[152:155], v[192:195], v[26:29]
	s_waitcnt lgkmcnt(0)
	v_mfma_f32_16x16x32_bf16 v[14:17], v[134:137], v[200:203], v[14:17]
	v_mfma_f32_16x16x32_bf16 v[10:13], v[152:155], v[200:203], v[10:13]
	s_setprio 0
	s_setprio 1
	v_mfma_f32_16x16x32_bf16 v[54:57], v[156:159], v[172:175], v[54:57]
	v_mfma_f32_16x16x32_bf16 v[50:53], v[164:167], v[172:175], v[50:53]
	v_mfma_f32_16x16x32_bf16 v[38:41], v[156:159], v[180:183], v[38:41]
	v_mfma_f32_16x16x32_bf16 v[34:37], v[164:167], v[180:183], v[34:37]
	v_mfma_f32_16x16x32_bf16 v[22:25], v[156:159], v[188:191], v[22:25]
	v_mfma_f32_16x16x32_bf16 v[18:21], v[164:167], v[188:191], v[18:21]
	v_mfma_f32_16x16x32_bf16 v[6:9], v[156:159], v[196:199], v[6:9]
	v_mfma_f32_16x16x32_bf16 v[2:5], v[164:167], v[196:199], v[2:5]
	v_mfma_f32_16x16x32_bf16 v[54:57], v[160:163], v[176:179], v[54:57]
	v_mfma_f32_16x16x32_bf16 v[50:53], v[168:171], v[176:179], v[50:53]
	v_mfma_f32_16x16x32_bf16 v[38:41], v[160:163], v[184:187], v[38:41]
	v_mfma_f32_16x16x32_bf16 v[34:37], v[168:171], v[184:187], v[34:37]
	v_mfma_f32_16x16x32_bf16 v[22:25], v[160:163], v[192:195], v[22:25]
	v_mfma_f32_16x16x32_bf16 v[18:21], v[168:171], v[192:195], v[18:21]
	v_mfma_f32_16x16x32_bf16 v[6:9], v[160:163], v[200:203], v[6:9]
	v_mfma_f32_16x16x32_bf16 v[2:5], v[168:171], v[200:203], v[2:5]
	s_setprio 0
	s_barrier
	s_add_i32 s73, s73, 2
	s_add_u32 s71, s71, 0x100
	s_addc_u32 s72, s72, 0
	s_cmp_gt_u32 s73, 13
	s_mov_b64 s[44:45], s[46:47]
	s_cbranch_scc0 .LBB0_367
	s_and_b64 vcc, exec, s[60:61]
	s_cbranch_vccz .LBB0_370
	s_barrier

.LBB0_493:
	s_waitcnt vmcnt(4)
	v_add_u32_e32 v110, 0x10000, v157
	v_add_u32_e32 v150, 0x14000, v157
	ds_read_b128 v[98:101], v110
	ds_read_b128 v[102:105], v110 offset:1024
	ds_read_b128 v[106:109], v110 offset:2048
	ds_read_b128 v[110:113], v110 offset:3072
	ds_read_b128 v[146:149], v150
	ds_read_b128 v[160:163], v150 offset:1024
	ds_read_b128 v[164:167], v150 offset:2048
	ds_read_b128 v[168:171], v150 offset:3072
	s_add_u32 s88, s60, 0x100
	s_addc_u32 s89, s61, 0
	s_cmp_eq_u32 s70, 12
	s_cselect_b32 s48, s27, s88
	s_cselect_b32 s49, s26, s89
	s_cselect_b32 s92, s47, s68
	s_cselect_b32 s93, s45, s69
	s_add_u32 s90, s48, 0x80
	s_addc_u32 s91, s49, 0
	ds_read_b128 v[172:175], v158
	ds_read_b128 v[176:179], v158 offset:1024
	ds_read_b128 v[180:183], v158 offset:2048
	ds_read_b128 v[184:187], v158 offset:3072
	ds_read_b128 v[188:191], v158 offset:4096
	ds_read_b128 v[192:195], v158 offset:5120
	ds_read_b128 v[196:199], v158 offset:6144
	ds_read_b128 v[200:203], v158 offset:7168
	s_add_u32 s60, s60, 0x40080
	s_addc_u32 s61, s61, 0
	s_mov_b32 m0, s84
	s_nop 0
	global_load_lds_dwordx4 v0, s[60:61]
	s_mov_b32 m0, s94
	s_nop 0
	global_load_lds_dwordx4 v153, s[60:61]
	s_waitcnt vmcnt(8)
	s_waitcnt lgkmcnt(0)
	s_barrier
	s_setprio 1
	s_waitcnt lgkmcnt(7)
	v_mfma_f32_16x16x32_bf16 v[142:145], v[98:101], v[172:175], v[142:145]
	v_mfma_f32_16x16x32_bf16 v[138:141], v[106:109], v[172:175], v[138:141]
	s_waitcnt lgkmcnt(5)
	v_mfma_f32_16x16x32_bf16 v[126:129], v[98:101], v[180:183], v[126:129]
	v_mfma_f32_16x16x32_bf16 v[122:125], v[106:109], v[180:183], v[122:125]
	s_waitcnt lgkmcnt(3)
	v_mfma_f32_16x16x32_bf16 v[94:97], v[98:101], v[188:191], v[94:97]
	v_mfma_f32_16x16x32_bf16 v[90:93], v[106:109], v[188:191], v[90:93]
	s_waitcnt lgkmcnt(1)
	v_mfma_f32_16x16x32_bf16 v[78:81], v[98:101], v[196:199], v[78:81]
	v_mfma_f32_16x16x32_bf16 v[74:77], v[106:109], v[196:199], v[74:77]
	v_mfma_f32_16x16x32_bf16 v[142:145], v[102:105], v[176:179], v[142:145]
	v_mfma_f32_16x16x32_bf16 v[138:141], v[110:113], v[176:179], v[138:141]
	v_mfma_f32_16x16x32_bf16 v[126:129], v[102:105], v[184:187], v[126:129]
	v_mfma_f32_16x16x32_bf16 v[122:125], v[110:113], v[184:187], v[122:125]
	v_mfma_f32_16x16x32_bf16 v[94:97], v[102:105], v[192:195], v[94:97]
	v_mfma_f32_16x16x32_bf16 v[90:93], v[110:113], v[192:195], v[90:93]
	s_waitcnt lgkmcnt(0)
	v_mfma_f32_16x16x32_bf16 v[78:81], v[102:105], v[200:203], v[78:81]
	v_mfma_f32_16x16x32_bf16 v[74:77], v[110:113], v[200:203], v[74:77]
	s_setprio 0
	s_setprio 1
	v_mfma_f32_16x16x32_bf16 v[134:137], v[146:149], v[172:175], v[134:137]
	v_mfma_f32_16x16x32_bf16 v[130:133], v[164:167], v[172:175], v[130:133]
	v_mfma_f32_16x16x32_bf16 v[118:121], v[146:149], v[180:183], v[118:121]
	v_mfma_f32_16x16x32_bf16 v[114:117], v[164:167], v[180:183], v[114:117]
	v_mfma_f32_16x16x32_bf16 v[86:89], v[146:149], v[188:191], v[86:89]
	v_mfma_f32_16x16x32_bf16 v[82:85], v[164:167], v[188:191], v[82:85]
	v_mfma_f32_16x16x32_bf16 v[70:73], v[146:149], v[196:199], v[70:73]
	v_mfma_f32_16x16x32_bf16 v[66:69], v[164:167], v[196:199], v[66:69]
	v_mfma_f32_16x16x32_bf16 v[134:137], v[160:163], v[176:179], v[134:137]
	v_mfma_f32_16x16x32_bf16 v[130:133], v[168:171], v[176:179], v[130:133]
	v_mfma_f32_16x16x32_bf16 v[118:121], v[160:163], v[184:187], v[118:121]
	v_mfma_f32_16x16x32_bf16 v[114:117], v[168:171], v[184:187], v[114:117]
	v_mfma_f32_16x16x32_bf16 v[86:89], v[160:163], v[192:195], v[86:89]
	v_mfma_f32_16x16x32_bf16 v[82:85], v[168:171], v[192:195], v[82:85]
	v_mfma_f32_16x16x32_bf16 v[70:73], v[160:163], v[200:203], v[70:73]
	v_mfma_f32_16x16x32_bf16 v[66:69], v[168:171], v[200:203], v[66:69]
	s_setprio 0
	s_barrier
	ds_read_b128 v[172:175], v158 offset:16384
	ds_read_b128 v[176:179], v158 offset:17408
	ds_read_b128 v[180:183], v158 offset:18432
	ds_read_b128 v[184:187], v158 offset:19456
	ds_read_b128 v[188:191], v158 offset:20480
	ds_read_b128 v[192:195], v158 offset:21504
	ds_read_b128 v[196:199], v158 offset:22528
	ds_read_b128 v[200:203], v158 offset:23552
	s_mov_b32 m0, s10
	s_nop 0
	global_load_lds_dwordx4 v152, s[92:93]
	s_mov_b32 m0, s11
	s_nop 0
	global_load_lds_dwordx4 v154, s[92:93]
	s_add_u32 s60, s92, 0x40000
	s_addc_u32 s61, s93, 0
	s_mov_b32 m0, s16
	s_nop 0
	global_load_lds_dwordx4 v152, s[60:61]
	s_mov_b32 m0, s17
	s_nop 0
	global_load_lds_dwordx4 v154, s[60:61]
	s_mov_b32 m0, s6
	s_nop 0
	global_load_lds_dwordx4 v0, s[48:49]
	s_mov_b32 m0, s18
	s_nop 0
	global_load_lds_dwordx4 v153, s[48:49]
	s_waitcnt vmcnt(8)
	s_waitcnt lgkmcnt(0)
	s_barrier
	s_setprio 1
	s_waitcnt lgkmcnt(7)
	v_mfma_f32_16x16x32_bf16 v[62:65], v[98:101], v[172:175], v[62:65]
	v_mfma_f32_16x16x32_bf16 v[58:61], v[106:109], v[172:175], v[58:61]
	s_waitcnt lgkmcnt(5)
	v_mfma_f32_16x16x32_bf16 v[50:53], v[98:101], v[180:183], v[50:53]
	v_mfma_f32_16x16x32_bf16 v[42:45], v[106:109], v[180:183], v[42:45]
	s_waitcnt lgkmcnt(3)
	v_mfma_f32_16x16x32_bf16 v[34:37], v[98:101], v[188:191], v[34:37]
	v_mfma_f32_16x16x32_bf16 v[26:29], v[106:109], v[188:191], v[26:29]
	s_waitcnt lgkmcnt(1)
	v_mfma_f32_16x16x32_bf16 v[18:21], v[98:101], v[196:199], v[18:21]
	v_mfma_f32_16x16x32_bf16 v[10:13], v[106:109], v[196:199], v[10:13]
	v_mfma_f32_16x16x32_bf16 v[62:65], v[102:105], v[176:179], v[62:65]
	v_mfma_f32_16x16x32_bf16 v[58:61], v[110:113], v[176:179], v[58:61]
	v_mfma_f32_16x16x32_bf16 v[50:53], v[102:105], v[184:187], v[50:53]
	v_mfma_f32_16x16x32_bf16 v[42:45], v[110:113], v[184:187], v[42:45]
	v_mfma_f32_16x16x32_bf16 v[34:37], v[102:105], v[192:195], v[34:37]
	v_mfma_f32_16x16x32_bf16 v[26:29], v[110:113], v[192:195], v[26:29]
	s_waitcnt lgkmcnt(0)
	v_mfma_f32_16x16x32_bf16 v[18:21], v[102:105], v[200:203], v[18:21]
	v_mfma_f32_16x16x32_bf16 v[10:13], v[110:113], v[200:203], v[10:13]
	s_setprio 0
	s_setprio 1
	v_mfma_f32_16x16x32_bf16 v[54:57], v[146:149], v[172:175], v[54:57]
	v_mfma_f32_16x16x32_bf16 v[46:49], v[164:167], v[172:175], v[46:49]
	v_mfma_f32_16x16x32_bf16 v[38:41], v[146:149], v[180:183], v[38:41]
	v_mfma_f32_16x16x32_bf16 v[30:33], v[164:167], v[180:183], v[30:33]
	v_mfma_f32_16x16x32_bf16 v[22:25], v[146:149], v[188:191], v[22:25]
	v_mfma_f32_16x16x32_bf16 v[14:17], v[164:167], v[188:191], v[14:17]
	v_mfma_f32_16x16x32_bf16 v[6:9], v[146:149], v[196:199], v[6:9]
	v_mfma_f32_16x16x32_bf16 v[2:5], v[164:167], v[196:199], v[2:5]
	v_mfma_f32_16x16x32_bf16 v[54:57], v[160:163], v[176:179], v[54:57]
	v_mfma_f32_16x16x32_bf16 v[46:49], v[168:171], v[176:179], v[46:49]
	v_mfma_f32_16x16x32_bf16 v[38:41], v[160:163], v[184:187], v[38:41]
	v_mfma_f32_16x16x32_bf16 v[30:33], v[168:171], v[184:187], v[30:33]
	v_mfma_f32_16x16x32_bf16 v[22:25], v[160:163], v[192:195], v[22:25]
	v_mfma_f32_16x16x32_bf16 v[14:17], v[168:171], v[192:195], v[14:17]
	v_mfma_f32_16x16x32_bf16 v[6:9], v[160:163], v[200:203], v[6:9]
	v_mfma_f32_16x16x32_bf16 v[2:5], v[168:171], v[200:203], v[2:5]
	s_setprio 0
	s_barrier
	v_add_u32_e32 v110, 0x18000, v157
	v_add_u32_e32 v150, 0x1c000, v157
	ds_read_b128 v[98:101], v110
	ds_read_b128 v[102:105], v110 offset:1024
	ds_read_b128 v[106:109], v110 offset:2048
	ds_read_b128 v[110:113], v110 offset:3072
	ds_read_b128 v[146:149], v150
	ds_read_b128 v[160:163], v150 offset:1024
	ds_read_b128 v[164:167], v150 offset:2048
	ds_read_b128 v[168:171], v150 offset:3072
	ds_read_b128 v[172:175], v158 offset:32768
	ds_read_b128 v[176:179], v158 offset:33792
	ds_read_b128 v[180:183], v158 offset:34816
	ds_read_b128 v[184:187], v158 offset:35840
	ds_read_b128 v[188:191], v158 offset:36864
	ds_read_b128 v[192:195], v158 offset:37888
	ds_read_b128 v[196:199], v158 offset:38912
	ds_read_b128 v[200:203], v158 offset:39936
	s_add_u32 s48, s48, 0x40000
	s_addc_u32 s49, s49, 0
	s_mov_b32 m0, s19
	s_nop 0
	global_load_lds_dwordx4 v0, s[48:49]
	s_mov_b32 m0, s20
	s_nop 0
	global_load_lds_dwordx4 v153, s[48:49]
	s_waitcnt vmcnt(8)
	s_waitcnt lgkmcnt(0)
	s_barrier
	s_setprio 1
	s_waitcnt lgkmcnt(7)
	v_mfma_f32_16x16x32_bf16 v[142:145], v[98:101], v[172:175], v[142:145]
	v_mfma_f32_16x16x32_bf16 v[138:141], v[106:109], v[172:175], v[138:141]
	s_waitcnt lgkmcnt(5)
	v_mfma_f32_16x16x32_bf16 v[126:129], v[98:101], v[180:183], v[126:129]
	v_mfma_f32_16x16x32_bf16 v[122:125], v[106:109], v[180:183], v[122:125]
	s_waitcnt lgkmcnt(3)
	v_mfma_f32_16x16x32_bf16 v[94:97], v[98:101], v[188:191], v[94:97]
	v_mfma_f32_16x16x32_bf16 v[90:93], v[106:109], v[188:191], v[90:93]
	s_waitcnt lgkmcnt(1)
	v_mfma_f32_16x16x32_bf16 v[78:81], v[98:101], v[196:199], v[78:81]
	v_mfma_f32_16x16x32_bf16 v[74:77], v[106:109], v[196:199], v[74:77]
	v_mfma_f32_16x16x32_bf16 v[142:145], v[102:105], v[176:179], v[142:145]
	v_mfma_f32_16x16x32_bf16 v[138:141], v[110:113], v[176:179], v[138:141]
	v_mfma_f32_16x16x32_bf16 v[126:129], v[102:105], v[184:187], v[126:129]
	v_mfma_f32_16x16x32_bf16 v[122:125], v[110:113], v[184:187], v[122:125]
	v_mfma_f32_16x16x32_bf16 v[94:97], v[102:105], v[192:195], v[94:97]
	v_mfma_f32_16x16x32_bf16 v[90:93], v[110:113], v[192:195], v[90:93]
	s_waitcnt lgkmcnt(0)
	v_mfma_f32_16x16x32_bf16 v[78:81], v[102:105], v[200:203], v[78:81]
	v_mfma_f32_16x16x32_bf16 v[74:77], v[110:113], v[200:203], v[74:77]
	s_setprio 0
	s_setprio 1
	v_mfma_f32_16x16x32_bf16 v[134:137], v[146:149], v[172:175], v[134:137]
	v_mfma_f32_16x16x32_bf16 v[130:133], v[164:167], v[172:175], v[130:133]
	v_mfma_f32_16x16x32_bf16 v[118:121], v[146:149], v[180:183], v[118:121]
	v_mfma_f32_16x16x32_bf16 v[114:117], v[164:167], v[180:183], v[114:117]
	v_mfma_f32_16x16x32_bf16 v[86:89], v[146:149], v[188:191], v[86:89]
	v_mfma_f32_16x16x32_bf16 v[82:85], v[164:167], v[188:191], v[82:85]
	v_mfma_f32_16x16x32_bf16 v[70:73], v[146:149], v[196:199], v[70:73]
	v_mfma_f32_16x16x32_bf16 v[66:69], v[164:167], v[196:199], v[66:69]
	v_mfma_f32_16x16x32_bf16 v[134:137], v[160:163], v[176:179], v[134:137]
	v_mfma_f32_16x16x32_bf16 v[130:133], v[168:171], v[176:179], v[130:133]
	v_mfma_f32_16x16x32_bf16 v[118:121], v[160:163], v[184:187], v[118:121]
	v_mfma_f32_16x16x32_bf16 v[114:117], v[168:171], v[184:187], v[114:117]
	v_mfma_f32_16x16x32_bf16 v[86:89], v[160:163], v[192:195], v[86:89]
	v_mfma_f32_16x16x32_bf16 v[82:85], v[168:171], v[192:195], v[82:85]
	v_mfma_f32_16x16x32_bf16 v[70:73], v[160:163], v[200:203], v[70:73]
	v_mfma_f32_16x16x32_bf16 v[66:69], v[168:171], v[200:203], v[66:69]
	s_setprio 0
	s_barrier
	ds_read_b128 v[172:175], v158 offset:49152
	ds_read_b128 v[176:179], v158 offset:50176
	ds_read_b128 v[180:183], v158 offset:51200
	ds_read_b128 v[184:187], v158 offset:52224
	ds_read_b128 v[188:191], v158 offset:53248
	ds_read_b128 v[192:195], v158 offset:54272
	ds_read_b128 v[196:199], v158 offset:55296
	ds_read_b128 v[200:203], v158 offset:56320
	s_add_u32 s48, s92, 0x80
	s_addc_u32 s49, s93, 0
	s_mov_b32 m0, s21
	s_nop 0
	global_load_lds_dwordx4 v152, s[48:49]
	s_mov_b32 m0, s22
	s_nop 0
	global_load_lds_dwordx4 v154, s[48:49]
	s_add_u32 s48, s92, 0x40080
	s_addc_u32 s49, s93, 0
	s_mov_b32 m0, s31
	s_nop 0
	global_load_lds_dwordx4 v152, s[48:49]
	s_mov_b32 m0, s33
	s_nop 0
	global_load_lds_dwordx4 v154, s[48:49]
	s_mov_b32 m0, s23
	s_nop 0
	global_load_lds_dwordx4 v0, s[90:91]
	s_mov_b32 m0, s28
	s_nop 0
	global_load_lds_dwordx4 v153, s[90:91]
	s_waitcnt vmcnt(8)
	s_waitcnt lgkmcnt(0)
	s_barrier
	s_setprio 1
	s_waitcnt lgkmcnt(7)
	v_mfma_f32_16x16x32_bf16 v[62:65], v[98:101], v[172:175], v[62:65]
	v_mfma_f32_16x16x32_bf16 v[58:61], v[106:109], v[172:175], v[58:61]
	s_waitcnt lgkmcnt(5)
	v_mfma_f32_16x16x32_bf16 v[50:53], v[98:101], v[180:183], v[50:53]
	v_mfma_f32_16x16x32_bf16 v[42:45], v[106:109], v[180:183], v[42:45]
	s_waitcnt lgkmcnt(3)
	v_mfma_f32_16x16x32_bf16 v[34:37], v[98:101], v[188:191], v[34:37]
	v_mfma_f32_16x16x32_bf16 v[26:29], v[106:109], v[188:191], v[26:29]
	s_waitcnt lgkmcnt(1)
	v_mfma_f32_16x16x32_bf16 v[18:21], v[98:101], v[196:199], v[18:21]
	v_mfma_f32_16x16x32_bf16 v[10:13], v[106:109], v[196:199], v[10:13]
	v_mfma_f32_16x16x32_bf16 v[62:65], v[102:105], v[176:179], v[62:65]
	v_mfma_f32_16x16x32_bf16 v[58:61], v[110:113], v[176:179], v[58:61]
	v_mfma_f32_16x16x32_bf16 v[50:53], v[102:105], v[184:187], v[50:53]
	v_mfma_f32_16x16x32_bf16 v[42:45], v[110:113], v[184:187], v[42:45]
	v_mfma_f32_16x16x32_bf16 v[34:37], v[102:105], v[192:195], v[34:37]
	v_mfma_f32_16x16x32_bf16 v[26:29], v[110:113], v[192:195], v[26:29]
	s_waitcnt lgkmcnt(0)
	v_mfma_f32_16x16x32_bf16 v[18:21], v[102:105], v[200:203], v[18:21]
	v_mfma_f32_16x16x32_bf16 v[10:13], v[110:113], v[200:203], v[10:13]
	s_setprio 0
	s_setprio 1
	v_mfma_f32_16x16x32_bf16 v[54:57], v[146:149], v[172:175], v[54:57]
	v_mfma_f32_16x16x32_bf16 v[46:49], v[164:167], v[172:175], v[46:49]
	v_mfma_f32_16x16x32_bf16 v[38:41], v[146:149], v[180:183], v[38:41]
	v_mfma_f32_16x16x32_bf16 v[30:33], v[164:167], v[180:183], v[30:33]
	v_mfma_f32_16x16x32_bf16 v[22:25], v[146:149], v[188:191], v[22:25]
	v_mfma_f32_16x16x32_bf16 v[14:17], v[164:167], v[188:191], v[14:17]
	v_mfma_f32_16x16x32_bf16 v[6:9], v[146:149], v[196:199], v[6:9]
	v_mfma_f32_16x16x32_bf16 v[2:5], v[164:167], v[196:199], v[2:5]
	v_mfma_f32_16x16x32_bf16 v[54:57], v[160:163], v[176:179], v[54:57]
	v_mfma_f32_16x16x32_bf16 v[46:49], v[168:171], v[176:179], v[46:49]
	v_mfma_f32_16x16x32_bf16 v[38:41], v[160:163], v[184:187], v[38:41]
	v_mfma_f32_16x16x32_bf16 v[30:33], v[168:171], v[184:187], v[30:33]
	v_mfma_f32_16x16x32_bf16 v[22:25], v[160:163], v[192:195], v[22:25]
	v_mfma_f32_16x16x32_bf16 v[14:17], v[168:171], v[192:195], v[14:17]
	v_mfma_f32_16x16x32_bf16 v[6:9], v[160:163], v[200:203], v[6:9]
	v_mfma_f32_16x16x32_bf16 v[2:5], v[168:171], v[200:203], v[2:5]
	s_setprio 0
	s_barrier
	s_add_i32 s70, s70, 2
	s_add_u32 s68, s68, 0x100
	s_addc_u32 s69, s69, 0
	s_cmp_gt_u32 s70, 13
	s_mov_b64 s[60:61], s[88:89]
	s_cbranch_scc0 .LBB0_493
	s_and_b64 vcc, exec, s[42:43]
	s_cbranch_vccz .LBB0_496
	s_barrier
